# prep K/V-cache loops (K convert, K zero rows, window copy) relocated into idle tail of IN phase on WGs>=90
# baseline (speedup 1.0000x reference)
; __device__ __forceinline__ unsigned pk2(float lo, float hi) { f32x2 v = {lo, hi}; bf16v2_t b = __builtin_convertvector(v, bf16v2_t); return __builtin_bit_cast(unsigned, b); }
; __device__ __forceinline__ void prep_phase(const Params& p, char* lds) {
;     ...
;     for (int i = gt; i < 128 * 128 * 16; i += NGT) {
;       const int c8 = i & 15, w = (i >> 4) & 127, b = i >> 11;
;       const float* s = ck + ((size_t)b * 128 + w) * 128 + c8 * 8;
;       const f32x4 a = *(const f32x4*)s, bq = *(const f32x4*)(s + 4);
;       u32x4 o; o.x = pk2(a.x, a.y); o.y = pk2(a.z, a.w); o.z = pk2(bq.x, bq.y); o.w = pk2(bq.z, bq.w);
;       *(u32x4*)(Ks + ((size_t)b * 144 + w) * 128 + c8 * 8) = o;
;     }
.LBB0_40:
	s_or_b64 exec, exec, s[0:1]
	v_readlane_b32 s4, v244, 0
	v_readlane_b32 s6, v244, 2
	s_mov_b32 s0, 0x40000
	v_readlane_b32 s5, v244, 1
	v_readlane_b32 s7, v244, 3
	s_add_u32 s24, s6, 0xad00000
	v_cmp_gt_i32_e64 s[0:1], s0, v186
	s_addc_u32 s25, s7, 0
	s_and_saveexec_b64 s[4:5], s[0:1]
	v_readlane_b32 s8, v244, 14
	v_readlane_b32 s14, v244, 20
	v_readlane_b32 s15, v244, 21
	v_readlane_b32 s12, v244, 18
	v_readlane_b32 s13, v244, 19
	s_mov_b64 s[14:15], s[24:25]
	v_readlane_b32 s9, v244, 15
	v_readlane_b32 s10, v244, 16
	v_readlane_b32 s11, v244, 17
	v_readlane_b32 s16, v244, 22
	v_readlane_b32 s17, v244, 23
	v_readlane_b32 s18, v244, 24
	v_readlane_b32 s19, v244, 25
	v_readlane_b32 s20, v244, 26
	v_readlane_b32 s21, v244, 27
	v_readlane_b32 s22, v244, 28
	v_readlane_b32 s23, v244, 29
	s_branch .LBB0_43
	v_readlane_b32 s3, v244, 33
	s_mov_b64 s[6:7], 0
	v_mov_b32_e32 v3, 0
	v_lshl_or_b32 v1, s3, 12, v43
	s_lshl_b32 s3, s33, 12
	s_mov_b32 s8, 0x3ffff
	v_mov_b32_e32 v4, v186

; __device__ __forceinline__ void prep_phase(const Params& p, char* lds) {
;     ...
;     for (int i = gt; i < 128 * 12 * 16; i += NGT) {
;       const int c8 = i & 15, r = (i >> 4) % 12, b = i / 192;
;       *(u32x4*)(Ks + ((size_t)b * 144 + 132 + r) * 128 + c8 * 8) = u32x4{0u, 0u, 0u, 0u};
;     }
.LBB0_43:
	s_or_b64 exec, exec, s[4:5]
	s_movk_i32 s3, 0x6000
	v_cmp_gt_i32_e32 vcc, s3, v186
	s_and_saveexec_b64 s[4:5], vcc
	s_branch .LBB0_46
	v_readlane_b32 s3, v244, 33
	v_mov_b32_e32 v3, 0
	s_mov_b64 s[6:7], 0
	v_lshl_or_b32 v1, s3, 12, v43
	s_lshl_b32 s3, s33, 12
	s_mov_b32 s8, 0x2aaaaaab
	s_movk_i32 s9, 0x90
	v_mov_b32_e32 v6, v3
	v_mov_b32_e32 v7, v3
	v_mov_b32_e32 v8, v3
	v_mov_b32_e32 v9, v3
	s_movk_i32 s10, 0x5fff
	v_mov_b32_e32 v4, v186

; __device__ __forceinline__ void prep_phase(const Params& p, char* lds) {
;     ...
;     for (int i = gt; i < 128 * 124 * 32; i += NGT) {
;       const int c4 = i & 31, w = (i >> 5) % 124, b = i / (124 * 32);
;       const size_t so = ((size_t)b * 128 + w + 4) * 128 + c4 * 4, dof = ((size_t)b * 128 + w) * 128 + c4 * 4;
;       *(f32x4*)(p.out + O_KS + dof) = *(const f32x4*)(ck + so);
;       *(f32x4*)(p.out + O_VS + dof) = *(const f32x4*)(cv + so);
;     }
.LBB0_52:
	s_or_b64 exec, exec, s[0:1]
	s_mov_b32 s0, 0x7c000
	v_cmp_gt_i32_e32 vcc, s0, v186
	s_and_saveexec_b64 s[0:1], vcc
	v_readlane_b32 s8, v244, 14
	v_readlane_b32 s16, v244, 22
	v_readlane_b32 s12, v244, 18
	v_readlane_b32 s13, v244, 19
	v_readlane_b32 s14, v244, 20
	v_readlane_b32 s15, v244, 21
	v_readlane_b32 s16, v244, 34
	v_readlane_b32 s9, v244, 15
	v_readlane_b32 s10, v244, 16
	v_readlane_b32 s11, v244, 17
	v_readlane_b32 s17, v244, 23
	v_readlane_b32 s18, v244, 24
	v_readlane_b32 s19, v244, 25
	v_readlane_b32 s20, v244, 26
	v_readlane_b32 s21, v244, 27
	v_readlane_b32 s22, v244, 28
	v_readlane_b32 s23, v244, 29
	s_branch .LBB0_55
	v_readlane_b32 s8, v244, 0
	v_readlane_b32 s9, v244, 1
	s_add_u32 s4, s8, 0x4300000
	s_addc_u32 s5, s9, 0
	v_readlane_b32 s10, v244, 2
	v_readlane_b32 s11, v244, 3
	s_add_u32 s6, s8, 0x4b00000
	v_readlane_b32 s3, v244, 33
	s_addc_u32 s7, s9, 0
	s_mov_b64 s[8:9], 0
	v_lshl_or_b32 v2, s3, 11, v1
	s_mov_b32 s3, 0x84210843
	s_movk_i32 s10, 0x7c
	s_mov_b32 s11, 0x7bfff
	v_mov_b32_e32 v3, v186

; __device__ __forceinline__ unsigned pk2(float lo, float hi) { f32x2 v = {lo, hi}; bf16v2_t b = __builtin_convertvector(v, bf16v2_t); return __builtin_bit_cast(unsigned, b); }
; __device__ __forceinline__ void prep_phase(const Params& p, char* lds) {
;     ...
;     for (int i = gt; i < 128 * 128 * 16; i += NGT) {
;       const int c8 = i & 15, w = (i >> 4) & 127, b = i >> 11;
;       const float* s = ck + ((size_t)b * 128 + w) * 128 + c8 * 8;
;       const f32x4 a = *(const f32x4*)s, bq = *(const f32x4*)(s + 4);
;       u32x4 o; o.x = pk2(a.x, a.y); o.y = pk2(a.z, a.w); o.z = pk2(bq.x, bq.y); o.w = pk2(bq.z, bq.w);
;       *(u32x4*)(Ks + ((size_t)b * 144 + w) * 128 + c8 * 8) = o;
;     }
;     for (int i = gt; i < 128 * 12 * 16; i += NGT) {
;       const int c8 = i & 15, r = (i >> 4) % 12, b = i / 192;
;       *(u32x4*)(Ks + ((size_t)b * 144 + 132 + r) * 128 + c8 * 8) = u32x4{0u, 0u, 0u, 0u};
;     }
.LBB0_448:
	s_waitcnt vmcnt(0)
	s_waitcnt vmcnt(0)
	s_barrier
	v_readlane_b32 s98, v244, 33
	s_nop 3
	s_cmp_eq_u32 s33, 0x100
	s_cselect_b32 s99, 90, 0
	s_cmp_lt_u32 s98, s99
	s_cbranch_scc1 .Lkvc_skip
	v_writelane_b32 v246, s0, 0
	v_writelane_b32 v246, s1, 1
	v_writelane_b32 v246, s2, 2
	v_writelane_b32 v246, s3, 3
	v_writelane_b32 v246, s4, 4
	v_writelane_b32 v246, s5, 5
	v_writelane_b32 v246, s6, 6
	v_writelane_b32 v246, s7, 7
	v_writelane_b32 v246, s8, 8
	v_writelane_b32 v246, s9, 9
	v_writelane_b32 v246, s10, 10
	v_writelane_b32 v246, s11, 11
	v_writelane_b32 v246, s12, 12
	v_writelane_b32 v246, s13, 13
	v_writelane_b32 v246, s14, 14
	v_writelane_b32 v246, s15, 15
	v_writelane_b32 v246, s16, 16
	v_writelane_b32 v246, s17, 17
	v_writelane_b32 v246, s18, 18
	v_writelane_b32 v246, s19, 19
	v_writelane_b32 v246, s20, 20
	v_writelane_b32 v246, s21, 21
	v_writelane_b32 v246, s22, 22
	v_writelane_b32 v246, s23, 23
	v_writelane_b32 v246, s24, 24
	v_writelane_b32 v246, s25, 25
	s_sub_u32 s98, s98, s99
	v_lshlrev_b32_e32 v247, 3, v0
	v_lshl_or_b32 v245, s98, 9, v0
	s_sub_u32 s100, s33, s99
	s_lshl_b32 s101, s100, 9
	v_readlane_b32 s4, v244, 0
	v_readlane_b32 s6, v244, 2
	s_mov_b32 s0, 0x40000
	v_readlane_b32 s5, v244, 1
	v_readlane_b32 s7, v244, 3
	s_add_u32 s24, s6, 0xad00000
	v_cmp_gt_i32_e64 s[0:1], s0, v245
	s_addc_u32 s25, s7, 0
	s_and_saveexec_b64 s[4:5], s[0:1]
	v_readlane_b32 s8, v244, 14
	v_readlane_b32 s14, v244, 20
	v_readlane_b32 s15, v244, 21
	v_readlane_b32 s12, v244, 18
	v_readlane_b32 s13, v244, 19
	s_mov_b64 s[14:15], s[24:25]
	v_readlane_b32 s9, v244, 15
	v_readlane_b32 s10, v244, 16
	v_readlane_b32 s11, v244, 17
	v_readlane_b32 s16, v244, 22
	v_readlane_b32 s17, v244, 23
	v_readlane_b32 s18, v244, 24
	v_readlane_b32 s19, v244, 25
	v_readlane_b32 s20, v244, 26
	v_readlane_b32 s21, v244, 27
	v_readlane_b32 s22, v244, 28
	v_readlane_b32 s23, v244, 29
	s_cbranch_execz .Lkvc_43
	v_readlane_b32 s3, v244, 33
	s_nop 3
	s_sub_u32 s3, s3, s99
	s_mov_b64 s[6:7], 0
	v_mov_b32_e32 v3, 0
	v_lshl_or_b32 v1, s3, 12, v247
	s_lshl_b32 s3, s100, 12
	s_mov_b32 s8, 0x3ffff
	v_mov_b32_e32 v4, v245
.Lkvc_42:
	v_ashrrev_i32_e32 v14, 11, v4
	v_ashrrev_i32_e32 v15, 31, v14
	v_bfe_u32 v2, v4, 4, 7
	v_lshlrev_b64 v[10:11], 16, v[14:15]
	v_mov_b32_e32 v7, v3
	v_and_b32_e32 v5, 0x78, v1
	v_lshlrev_b32_e32 v6, 9, v2
	v_lshl_add_u64 v[10:11], s[12:13], 0, v[10:11]
	v_mov_b32_e32 v9, v3
	v_lshlrev_b32_e32 v8, 2, v5
	v_lshl_add_u64 v[6:7], v[10:11], 0, v[6:7]
	v_lshl_add_u64 v[10:11], v[6:7], 0, v[8:9]
	global_load_dwordx4 v[6:9], v[10:11], off
	s_nop 0
	global_load_dwordx4 v[10:13], v[10:11], off offset:16
	v_mul_hi_i32_i24_e32 v15, 0x90, v14
	v_mul_i32_i24_e32 v14, 0x90, v14
	v_lshl_add_u64 v[14:15], v[14:15], 0, v[2:3]
	v_add_u32_e32 v4, s101, v4
	v_lshlrev_b64 v[14:15], 8, v[14:15]
	v_cmp_lt_i32_e32 vcc, s8, v4
	v_lshlrev_b32_e32 v2, 1, v5
	v_lshl_add_u64 v[14:15], s[14:15], 0, v[14:15]
	v_add_u32_e32 v1, s3, v1
	s_or_b64 s[6:7], vcc, s[6:7]
	v_lshl_add_u64 v[14:15], v[14:15], 0, v[2:3]
	s_waitcnt vmcnt(1)
	v_cvt_pk_bf16_f32 v6, v6, v7
	v_cvt_pk_bf16_f32 v7, v8, v9
	s_waitcnt vmcnt(0)
	v_cvt_pk_bf16_f32 v8, v10, v11
	v_cvt_pk_bf16_f32 v9, v12, v13
	global_store_dwordx4 v[14:15], v[6:9], off
	s_andn2_b64 exec, exec, s[6:7]
	s_cbranch_execnz .Lkvc_42
.Lkvc_43:
	s_or_b64 exec, exec, s[4:5]
	s_movk_i32 s3, 0x6000
	v_cmp_gt_i32_e32 vcc, s3, v245
	s_and_saveexec_b64 s[4:5], vcc
	s_cbranch_execz .Lkvc_46
	v_readlane_b32 s3, v244, 33
	s_nop 3
	s_sub_u32 s3, s3, s99
	v_mov_b32_e32 v3, 0
	s_mov_b64 s[6:7], 0
	v_lshl_or_b32 v1, s3, 12, v247
	s_lshl_b32 s3, s100, 12
	s_mov_b32 s8, 0x2aaaaaab
	s_movk_i32 s9, 0x90
	v_mov_b32_e32 v6, v3
	v_mov_b32_e32 v7, v3
	v_mov_b32_e32 v8, v3
	v_mov_b32_e32 v9, v3
	s_movk_i32 s10, 0x5fff
	v_mov_b32_e32 v4, v245
; __device__ __forceinline__ unsigned pk2(float lo, float hi) { f32x2 v = {lo, hi}; bf16v2_t b = __builtin_convertvector(v, bf16v2_t); return __builtin_bit_cast(unsigned, b); }
; __device__ __forceinline__ void prep_phase(const Params& p, char* lds) {
;     ...
;     for (int i = gt; i < 128 * 12 * 16; i += NGT) {
;       const int c8 = i & 15, r = (i >> 4) % 12, b = i / 192;
;       *(u32x4*)(Ks + ((size_t)b * 144 + 132 + r) * 128 + c8 * 8) = u32x4{0u, 0u, 0u, 0u};
;     }
;     for (int i = gt; i < 128 * 16 * 128; i += NGT) {
;       const int kvd = i & 127, w8 = (i >> 7) & 15, b = i >> 11;
;       const float* s = cv + ((size_t)b * 128 + w8 * 8) * 128 + kvd;
;       u32x4 o; o.x = pk2(s[0], s[128]); o.y = pk2(s[256], s[384]); o.z = pk2(s[512], s[640]); o.w = pk2(s[768], s[896]);
;       *(u32x4*)(Vts + ((size_t)b * 128 + kvd) * 144 + w8 * 8) = o;
;     }
;     for (int i = gt; i < 128 * 128 * 3; i += NGT) {
;       const int q = i % 3, r = i / 3;
;       *(u32x2*)(Vts + (size_t)r * 144 + 132 + q * 4) = u32x2{0u, 0u};
;     }
;     for (int i = gt; i < 128 * 124 * 32; i += NGT) {
;       const int c4 = i & 31, w = (i >> 5) % 124, b = i / (124 * 32);
;       const size_t so = ((size_t)b * 128 + w + 4) * 128 + c4 * 4, dof = ((size_t)b * 128 + w) * 128 + c4 * 4;
;       *(f32x4*)(p.out + O_KS + dof) = *(const f32x4*)(ck + so);
;       *(f32x4*)(p.out + O_VS + dof) = *(const f32x4*)(cv + so);
;     }
.Lkvc_45:
	v_ashrrev_i32_e32 v5, 4, v4
	v_mul_hi_i32 v2, v4, s8
	v_and_b32_e32 v10, 0x78, v1
	v_mul_hi_i32 v11, v5, s8
	v_lshrrev_b32_e32 v12, 31, v2
	v_ashrrev_i32_e32 v13, 5, v2
	v_lshlrev_b32_e32 v2, 1, v10
	v_lshrrev_b32_e32 v10, 31, v11
	v_lshrrev_b32_e32 v11, 1, v11
	v_add_u32_e32 v10, v11, v10
	v_mul_lo_u32 v10, v10, 12
	v_sub_u32_e32 v10, v5, v10
	v_add_u32_e32 v12, v13, v12
	v_ashrrev_i32_e32 v11, 31, v10
	v_mad_i64_i32 v[10:11], s[12:13], v12, s9, v[10:11]
	v_lshlrev_b64 v[10:11], 8, v[10:11]
	v_add_u32_e32 v4, s101, v4
	v_lshl_add_u64 v[10:11], s[14:15], 0, v[10:11]
	v_cmp_lt_i32_e32 vcc, s10, v4
	v_lshl_add_u64 v[10:11], v[10:11], 0, v[2:3]
	s_or_b64 s[6:7], vcc, s[6:7]
	v_add_co_u32_e32 v10, vcc, 0x8000, v10
	v_add_u32_e32 v1, s3, v1
	s_nop 0
	v_addc_co_u32_e32 v11, vcc, 0, v11, vcc
	global_store_dwordx4 v[10:11], v[6:9], off offset:1024
	s_andn2_b64 exec, exec, s[6:7]
	s_cbranch_execnz .Lkvc_45
.Lkvc_46:
	s_or_b64 exec, exec, s[4:5]
	v_lshlrev_b32_e32 v1, 2, v0
	s_mov_b32 s0, 0x7c000
	v_cmp_gt_i32_e32 vcc, s0, v245
	s_and_saveexec_b64 s[0:1], vcc
	v_readlane_b32 s8, v244, 14
	v_readlane_b32 s16, v244, 22
	v_readlane_b32 s12, v244, 18
	v_readlane_b32 s13, v244, 19
	v_readlane_b32 s14, v244, 20
	v_readlane_b32 s15, v244, 21
	v_readlane_b32 s16, v244, 34
	v_readlane_b32 s9, v244, 15
	v_readlane_b32 s10, v244, 16
	v_readlane_b32 s11, v244, 17
	v_readlane_b32 s17, v244, 23
	v_readlane_b32 s18, v244, 24
	v_readlane_b32 s19, v244, 25
	v_readlane_b32 s20, v244, 26
	v_readlane_b32 s21, v244, 27
	v_readlane_b32 s22, v244, 28
	v_readlane_b32 s23, v244, 29
	s_cbranch_execz .Lkvc_55
	v_readlane_b32 s8, v244, 0
	v_readlane_b32 s9, v244, 1
	s_add_u32 s4, s8, 0x4300000
	s_addc_u32 s5, s9, 0
	v_readlane_b32 s10, v244, 2
	v_readlane_b32 s11, v244, 3
	s_add_u32 s6, s8, 0x4b00000
	v_readlane_b32 s3, v244, 33
	s_nop 3
	s_sub_u32 s3, s3, s99
	s_addc_u32 s7, s9, 0
	s_mov_b64 s[8:9], 0
	v_lshl_or_b32 v2, s3, 11, v1
	s_mov_b32 s3, 0x84210843
	s_movk_i32 s10, 0x7c
	s_mov_b32 s11, 0x7bfff
	v_mov_b32_e32 v3, v245
.Lkvc_54:
	v_ashrrev_i32_e32 v6, 5, v3
	v_mul_hi_i32 v4, v3, s3
	v_mul_hi_i32 v5, v6, s3
	v_add_u32_e32 v4, v4, v3
	v_add_u32_e32 v5, v5, v6
	v_lshrrev_b32_e32 v7, 31, v4
	v_ashrrev_i32_e32 v4, 11, v4
	v_lshrrev_b32_e32 v8, 31, v5
	v_ashrrev_i32_e32 v5, 6, v5
	v_add_u32_e32 v4, v4, v7
	v_add_u32_e32 v7, v5, v8
	v_mul_lo_u32 v7, v7, s10
	v_sub_u32_e32 v6, v6, v7
	v_ashrrev_i32_e32 v5, 31, v4
	v_ashrrev_i32_e32 v7, 31, v6
	v_lshlrev_b64 v[4:5], 14, v[4:5]
	v_lshlrev_b64 v[6:7], 7, v[6:7]
	v_lshl_add_u64 v[4:5], v[6:7], 0, v[4:5]
	v_and_or_b32 v4, v2, s10, v4
	v_lshlrev_b64 v[8:9], 2, v[4:5]
	v_lshl_add_u64 v[4:5], s[12:13], 0, v[8:9]
	global_load_dwordx4 v[4:7], v[4:5], off offset:2048
	v_lshl_add_u64 v[10:11], s[4:5], 0, v[8:9]
	v_lshl_add_u64 v[12:13], s[14:15], 0, v[8:9]
	v_add_u32_e32 v3, s101, v3
	v_cmp_lt_i32_e32 vcc, s11, v3
	s_or_b64 s[8:9], vcc, s[8:9]
	v_add_u32_e32 v2, s16, v2
	v_lshl_add_u64 v[8:9], s[6:7], 0, v[8:9]
	s_waitcnt vmcnt(0)
	global_store_dwordx4 v[10:11], v[4:7], off
	global_load_dwordx4 v[4:7], v[12:13], off offset:2048
	s_waitcnt vmcnt(0)
	global_store_dwordx4 v[8:9], v[4:7], off
	s_andn2_b64 exec, exec, s[8:9]
	s_cbranch_execnz .Lkvc_54
.Lkvc_55:
	s_or_b64 exec, exec, s[0:1]
	v_readlane_b32 s0, v246, 0
	v_readlane_b32 s1, v246, 1
	v_readlane_b32 s2, v246, 2
	v_readlane_b32 s3, v246, 3
	v_readlane_b32 s4, v246, 4
	v_readlane_b32 s5, v246, 5
	v_readlane_b32 s6, v246, 6
	v_readlane_b32 s7, v246, 7
	v_readlane_b32 s8, v246, 8
	v_readlane_b32 s9, v246, 9
	v_readlane_b32 s10, v246, 10
	v_readlane_b32 s11, v246, 11
	v_readlane_b32 s12, v246, 12
	v_readlane_b32 s13, v246, 13
	v_readlane_b32 s14, v246, 14
	v_readlane_b32 s15, v246, 15
	v_readlane_b32 s16, v246, 16
	v_readlane_b32 s17, v246, 17
	v_readlane_b32 s18, v246, 18
	v_readlane_b32 s19, v246, 19
	v_readlane_b32 s20, v246, 20
	v_readlane_b32 s21, v246, 21
	v_readlane_b32 s22, v246, 22
	v_readlane_b32 s23, v246, 23
	v_readlane_b32 s24, v246, 24
	v_readlane_b32 s25, v246, 25
	s_waitcnt vmcnt(0)
	s_barrier
.Lkvc_skip:
	s_mov_b64 s[0:1], exec
	v_readlane_b32 s4, v244, 12
	v_readlane_b32 s5, v244, 13
	s_and_b64 s[4:5], s[0:1], s[4:5]
	s_mov_b64 exec, s[4:5]
	s_cbranch_execz .LBB0_500
	s_add_i32 s3, 0, 0x20000
	v_mov_b32_e32 v2, s3
	s_waitcnt vmcnt(0) expcnt(0) lgkmcnt(0)
	ds_read_b32 v4, v2
	s_add_i32 s3, 0, 0x20004
	v_mov_b32_e32 v2, s3
	ds_read_b32 v2, v2
	s_waitcnt lgkmcnt(1)
	v_cmp_ne_u32_e32 vcc, 0, v4
	s_cbranch_vccnz .LBB0_464
	v_readlane_b32 s6, v244, 31
	v_readlane_b32 s7, v244, 32
	s_load_dwordx2 s[4:5], s[6:7], 0x4
	s_mov_b32 s3, 1
	v_mov_b32_e32 v18, 0
	s_waitcnt lgkmcnt(0)
	s_mul_i32 s10, s4, s33
	s_mul_i32 s10, s10, s5
	s_branch .LBB0_452

; __global__ void __launch_bounds__(512) fwd_megakernel(Params p) {
	.amdhsa_kernel _Z14fwd_megakernel6Params
		.amdhsa_group_segment_fixed_size 0
		.amdhsa_private_segment_fixed_size 0
		.amdhsa_kernarg_size 496
		.amdhsa_user_sgpr_count 2
		.amdhsa_user_sgpr_dispatch_ptr 0
		.amdhsa_user_sgpr_queue_ptr 0
		.amdhsa_user_sgpr_kernarg_segment_ptr 1
		.amdhsa_user_sgpr_dispatch_id 0
		.amdhsa_user_sgpr_kernarg_preload_length 0
		.amdhsa_user_sgpr_kernarg_preload_offset 0
		.amdhsa_user_sgpr_private_segment_size 0
		.amdhsa_uses_dynamic_stack 0
		.amdhsa_enable_private_segment 0
		.amdhsa_system_sgpr_workgroup_id_x 1
		.amdhsa_system_sgpr_workgroup_id_y 0
		.amdhsa_system_sgpr_workgroup_id_z 0
		.amdhsa_system_sgpr_workgroup_info 0
		.amdhsa_system_vgpr_workitem_id 0
		.amdhsa_next_free_vgpr 248
		.amdhsa_next_free_sgpr 102
		.amdhsa_accum_offset 248
		.amdhsa_reserve_vcc 1
		.amdhsa_float_round_mode_32 0
		.amdhsa_float_round_mode_16_64 0
		.amdhsa_float_denorm_mode_32 3
		.amdhsa_float_denorm_mode_16_64 3
		.amdhsa_dx10_clamp 1
		.amdhsa_ieee_mode 1
		.amdhsa_fp16_overflow 0
		.amdhsa_tg_split 0
		.amdhsa_exception_fp_ieee_invalid_op 0
		.amdhsa_exception_fp_denorm_src 0
		.amdhsa_exception_fp_ieee_div_zero 0
		.amdhsa_exception_fp_ieee_overflow 0
		.amdhsa_exception_fp_ieee_underflow 0
		.amdhsa_exception_fp_ieee_inexact 0
		.amdhsa_exception_int_div_zero 0
	.end_amdhsa_kernel

; __global__ void __launch_bounds__(512) fwd_megakernel(Params p) {
.Lfunc_end0:
	.size	_Z14fwd_megakernel6Params, .Lfunc_end0-_Z14fwd_megakernel6Params
	.set _Z14fwd_megakernel6Params.num_vgpr, 248
	.set _Z14fwd_megakernel6Params.num_agpr, 0
	.set _Z14fwd_megakernel6Params.numbered_sgpr, 102
	.set _Z14fwd_megakernel6Params.num_named_barrier, 0
	.set _Z14fwd_megakernel6Params.private_seg_size, 0
	.set _Z14fwd_megakernel6Params.uses_vcc, 1
	.set _Z14fwd_megakernel6Params.uses_flat_scratch, 0
	.set _Z14fwd_megakernel6Params.has_dyn_sized_stack, 0
	.set _Z14fwd_megakernel6Params.has_recursion, 0
	.set _Z14fwd_megakernel6Params.has_indirect_call, 0

; __global__ void __launch_bounds__(512) fwd_megakernel(Params p) {
amdhsa.kernels:
  - .agpr_count:     0
    .args:
      - .offset:         0
        .size:           240
        .value_kind:     by_value
      - .offset:         240
        .size:           4
        .value_kind:     hidden_block_count_x
      - .offset:         244
        .size:           4
        .value_kind:     hidden_block_count_y
      - .offset:         248
        .size:           4
        .value_kind:     hidden_block_count_z
      - .offset:         252
        .size:           2
        .value_kind:     hidden_group_size_x
      - .offset:         254
        .size:           2
        .value_kind:     hidden_group_size_y
      - .offset:         256
        .size:           2
        .value_kind:     hidden_group_size_z
      - .offset:         258
        .size:           2
        .value_kind:     hidden_remainder_x
      - .offset:         260
        .size:           2
        .value_kind:     hidden_remainder_y
      - .offset:         262
        .size:           2
        .value_kind:     hidden_remainder_z
      - .offset:         280
        .size:           8
        .value_kind:     hidden_global_offset_x
      - .offset:         288
        .size:           8
        .value_kind:     hidden_global_offset_y
      - .offset:         296
        .size:           8
        .value_kind:     hidden_global_offset_z
      - .offset:         304
        .size:           2
        .value_kind:     hidden_grid_dims
      - .offset:         360
        .size:           4
        .value_kind:     hidden_dynamic_lds_size
    .group_segment_fixed_size: 0
    .kernarg_segment_align: 8
    .kernarg_segment_size: 496
    .language:       OpenCL C
    .language_version:
      - 2
      - 0
    .max_flat_workgroup_size: 512
    .name:           _Z14fwd_megakernel6Params
    .private_segment_fixed_size: 0
    .sgpr_count:     108
    .sgpr_spill_count: 68
    .symbol:         _Z14fwd_megakernel6Params.kd
    .uniform_work_group_size: 1
    .uses_dynamic_stack: false
    .vgpr_count:     248
    .vgpr_spill_count: 0
    .wavefront_size: 64
